# grid barrier poll loop without s_sleep (32 pollers per replicated counter)
# baseline (speedup 1.0000x reference)
.Lgb0_poll:
	global_load_dword v4, v0, s[8:9] sc1
	s_waitcnt vmcnt(0)
	v_readfirstlane_b32 s0, v4
	s_sub_i32 s0, s0, s6
	s_cmp_ge_i32 s0, 0
	s_cbranch_scc1 .Lgb0_rel
	s_add_i32 s7, s7, 1
	s_cmp_lt_u32 s7, 0x40000
	s_cbranch_scc1 .Lgb0_poll

.Lgb4_poll:
	global_load_dword v4, v0, s[8:9] sc1
	s_waitcnt vmcnt(0)
	v_readfirstlane_b32 s0, v4
	s_sub_i32 s0, s0, s4
	s_cmp_ge_i32 s0, 0
	s_cbranch_scc1 .Lgb4_rel
	s_add_i32 s5, s5, 1
	s_cmp_lt_u32 s5, 0x40000
	s_cbranch_scc1 .Lgb4_poll
